# GEMM K-loop: per-iteration scalar pointer bookkeeping moved from right after the barriers to just before the load-segment waits, so the fragment reads issue first
# baseline (speedup 1.0000x reference)
.LBB0_246:
	s_andn2_b64 vcc, exec, s[18:19]
	s_cbranch_vccnz .Lk_zero_skip
	v_add_u32_e32 v236, 0x10000, v227
	v_add_u32_e32 v237, 0x14000, v227
	v_add_u32_e32 v238, 0x18000, v227
	v_add_u32_e32 v239, 0x1c000, v227
	s_add_u32 s44, s44, 0x80
	s_addc_u32 s45, s45, 0
	s_add_u32 s23, s46, 0x100
	s_addc_u32 s48, s47, 0
	s_mov_b32 s46, 0
	ds_read_b128 v[128:131], v236
	ds_read_b128 v[132:135], v236 offset:1024
	ds_read_b128 v[136:139], v236 offset:2048
	ds_read_b128 v[140:143], v236 offset:3072
	ds_read_b128 v[144:147], v237
	ds_read_b128 v[148:151], v237 offset:1024
	ds_read_b128 v[174:177], v237 offset:2048
	ds_read_b128 v[178:181], v237 offset:3072
	s_add_i32 m0, s50, 0xc000
	ds_read_b128 v[182:185], v230
	ds_read_b128 v[186:189], v230 offset:1024
	ds_read_b128 v[190:193], v230 offset:2048
	ds_read_b128 v[194:197], v230 offset:3072
	ds_read_b128 v[198:201], v230 offset:4096
	ds_read_b128 v[202:205], v230 offset:5120
	ds_read_b128 v[206:209], v230 offset:6144
	ds_read_b128 v[232:235], v230 offset:7168
	global_load_lds_dwordx4 v170, s[44:45]
	s_add_i32 m0, s50, 0xe000
	s_nop 0
	global_load_lds_dwordx4 v172, s[44:45]
	s_add_i32 s49, s46, 2
	s_add_u32 s69, s44, 0x80
	s_addc_u32 s47, s45, 0
	s_add_i32 s80, 0, 0x10000
	s_cmp_eq_u32 s90, s46
	s_cselect_b32 s47, s65, s47
	s_cselect_b32 s46, s64, s69
	s_cselect_b32 s71, s67, s48
	s_cselect_b32 s70, s66, s23
	s_add_i32 s69, 0, 0x14000
	s_waitcnt vmcnt(8)
	s_waitcnt lgkmcnt(0)
	s_barrier
	s_setprio 1
	s_waitcnt lgkmcnt(0)
	v_mfma_f32_16x16x32_bf16 v[16:19], v[128:131], v[182:185], 0
	v_mfma_f32_16x16x32_bf16 v[28:31], v[136:139], v[182:185], 0
	v_mfma_f32_16x16x32_bf16 v[12:15], v[128:131], v[190:193], 0
	v_mfma_f32_16x16x32_bf16 v[8:11], v[136:139], v[190:193], 0
	v_mfma_f32_16x16x32_bf16 v[124:127], v[128:131], v[198:201], 0
	v_mfma_f32_16x16x32_bf16 v[120:123], v[136:139], v[198:201], 0
	v_mfma_f32_16x16x32_bf16 v[108:111], v[128:131], v[206:209], 0
	v_mfma_f32_16x16x32_bf16 v[104:107], v[136:139], v[206:209], 0
	v_mfma_f32_16x16x32_bf16 v[16:19], v[132:135], v[186:189], v[16:19]
	v_mfma_f32_16x16x32_bf16 v[28:31], v[140:143], v[186:189], v[28:31]
	v_mfma_f32_16x16x32_bf16 v[12:15], v[132:135], v[194:197], v[12:15]
	v_mfma_f32_16x16x32_bf16 v[8:11], v[140:143], v[194:197], v[8:11]
	v_mfma_f32_16x16x32_bf16 v[124:127], v[132:135], v[202:205], v[124:127]
	v_mfma_f32_16x16x32_bf16 v[120:123], v[140:143], v[202:205], v[120:123]
	v_mfma_f32_16x16x32_bf16 v[108:111], v[132:135], v[232:235], v[108:111]
	v_mfma_f32_16x16x32_bf16 v[104:107], v[140:143], v[232:235], v[104:107]
	s_setprio 0
	s_setprio 1
	v_mfma_f32_16x16x32_bf16 v[24:27], v[144:147], v[182:185], 0
	v_mfma_f32_16x16x32_bf16 v[20:23], v[174:177], v[182:185], 0
	v_mfma_f32_16x16x32_bf16 v[4:7], v[144:147], v[190:193], 0
	v_mfma_f32_16x16x32_bf16 v[0:3], v[174:177], v[190:193], 0
	v_mfma_f32_16x16x32_bf16 v[116:119], v[144:147], v[198:201], 0
	v_mfma_f32_16x16x32_bf16 v[112:115], v[174:177], v[198:201], 0
	v_mfma_f32_16x16x32_bf16 v[100:103], v[144:147], v[206:209], 0
	v_mfma_f32_16x16x32_bf16 v[96:99], v[174:177], v[206:209], 0
	v_mfma_f32_16x16x32_bf16 v[24:27], v[148:151], v[186:189], v[24:27]
	v_mfma_f32_16x16x32_bf16 v[20:23], v[178:181], v[186:189], v[20:23]
	v_mfma_f32_16x16x32_bf16 v[4:7], v[148:151], v[194:197], v[4:7]
	v_mfma_f32_16x16x32_bf16 v[0:3], v[178:181], v[194:197], v[0:3]
	v_mfma_f32_16x16x32_bf16 v[116:119], v[148:151], v[202:205], v[116:119]
	v_mfma_f32_16x16x32_bf16 v[112:115], v[178:181], v[202:205], v[112:115]
	v_mfma_f32_16x16x32_bf16 v[100:103], v[148:151], v[232:235], v[100:103]
	v_mfma_f32_16x16x32_bf16 v[96:99], v[178:181], v[232:235], v[96:99]
	s_setprio 0
	s_barrier
	s_add_i32 s80, s80, s3
	s_mov_b32 m0, s80
	ds_read_b128 v[182:185], v230 offset:16384
	ds_read_b128 v[186:189], v230 offset:17408
	ds_read_b128 v[190:193], v230 offset:18432
	ds_read_b128 v[194:197], v230 offset:19456
	ds_read_b128 v[198:201], v230 offset:20480
	ds_read_b128 v[202:205], v230 offset:21504
	ds_read_b128 v[206:209], v230 offset:22528
	ds_read_b128 v[232:235], v230 offset:23552
	global_load_lds_dwordx4 v160, s[70:71]
	s_add_i32 m0, s80, 0x2000
	s_add_i32 s69, s69, s3
	global_load_lds_dwordx4 v164, s[70:71]
	s_add_u32 s70, s70, s26
	s_addc_u32 s71, s71, 0
	s_mov_b32 m0, s69
	s_nop 0
	global_load_lds_dwordx4 v160, s[70:71]
	s_add_i32 m0, s69, 0x2000
	s_nop 0
	global_load_lds_dwordx4 v164, s[70:71]
	s_mov_b32 m0, s50
	s_nop 0
	global_load_lds_dwordx4 v158, s[46:47]
	s_mov_b32 m0, s51
	s_nop 0
	global_load_lds_dwordx4 v162, s[46:47]
	s_waitcnt vmcnt(8)
	s_waitcnt lgkmcnt(0)
	s_barrier
	s_setprio 1
	s_waitcnt lgkmcnt(0)
	v_mfma_f32_16x16x32_bf16 v[92:95], v[128:131], v[182:185], 0
	v_mfma_f32_16x16x32_bf16 v[88:91], v[136:139], v[182:185], 0
	v_mfma_f32_16x16x32_bf16 v[76:79], v[128:131], v[190:193], 0
	v_mfma_f32_16x16x32_bf16 v[72:75], v[136:139], v[190:193], 0
	v_mfma_f32_16x16x32_bf16 v[60:63], v[128:131], v[198:201], 0
	v_mfma_f32_16x16x32_bf16 v[56:59], v[136:139], v[198:201], 0
	v_mfma_f32_16x16x32_bf16 v[44:47], v[128:131], v[206:209], 0
	v_mfma_f32_16x16x32_bf16 v[40:43], v[136:139], v[206:209], 0
	v_mfma_f32_16x16x32_bf16 v[92:95], v[132:135], v[186:189], v[92:95]
	v_mfma_f32_16x16x32_bf16 v[88:91], v[140:143], v[186:189], v[88:91]
	v_mfma_f32_16x16x32_bf16 v[76:79], v[132:135], v[194:197], v[76:79]
	v_mfma_f32_16x16x32_bf16 v[72:75], v[140:143], v[194:197], v[72:75]
	v_mfma_f32_16x16x32_bf16 v[60:63], v[132:135], v[202:205], v[60:63]
	v_mfma_f32_16x16x32_bf16 v[56:59], v[140:143], v[202:205], v[56:59]
	v_mfma_f32_16x16x32_bf16 v[44:47], v[132:135], v[232:235], v[44:47]
	v_mfma_f32_16x16x32_bf16 v[40:43], v[140:143], v[232:235], v[40:43]
	s_setprio 0
	s_setprio 1
	v_mfma_f32_16x16x32_bf16 v[84:87], v[144:147], v[182:185], 0
	v_mfma_f32_16x16x32_bf16 v[80:83], v[174:177], v[182:185], 0
	v_mfma_f32_16x16x32_bf16 v[68:71], v[144:147], v[190:193], 0
	v_mfma_f32_16x16x32_bf16 v[64:67], v[174:177], v[190:193], 0
	v_mfma_f32_16x16x32_bf16 v[52:55], v[144:147], v[198:201], 0
	v_mfma_f32_16x16x32_bf16 v[48:51], v[174:177], v[198:201], 0
	v_mfma_f32_16x16x32_bf16 v[36:39], v[144:147], v[206:209], 0
	v_mfma_f32_16x16x32_bf16 v[32:35], v[174:177], v[206:209], 0
	v_mfma_f32_16x16x32_bf16 v[84:87], v[148:151], v[186:189], v[84:87]
	v_mfma_f32_16x16x32_bf16 v[80:83], v[178:181], v[186:189], v[80:83]
	v_mfma_f32_16x16x32_bf16 v[68:71], v[148:151], v[194:197], v[68:71]
	v_mfma_f32_16x16x32_bf16 v[64:67], v[178:181], v[194:197], v[64:67]
	v_mfma_f32_16x16x32_bf16 v[52:55], v[148:151], v[202:205], v[52:55]
	v_mfma_f32_16x16x32_bf16 v[48:51], v[178:181], v[202:205], v[48:51]
	v_mfma_f32_16x16x32_bf16 v[36:39], v[148:151], v[232:235], v[36:39]
	v_mfma_f32_16x16x32_bf16 v[32:35], v[178:181], v[232:235], v[32:35]
	s_setprio 0
	s_barrier
	ds_read_b128 v[128:131], v238
	ds_read_b128 v[132:135], v238 offset:1024
	ds_read_b128 v[136:139], v238 offset:2048
	ds_read_b128 v[140:143], v238 offset:3072
	ds_read_b128 v[144:147], v239
	ds_read_b128 v[148:151], v239 offset:1024
	ds_read_b128 v[174:177], v239 offset:2048
	ds_read_b128 v[178:181], v239 offset:3072
	s_add_u32 s46, s46, s26
	s_addc_u32 s47, s47, 0
	s_mov_b32 m0, s8
	ds_read_b128 v[182:185], v230 offset:32768
	ds_read_b128 v[186:189], v230 offset:33792
	ds_read_b128 v[190:193], v230 offset:34816
	ds_read_b128 v[194:197], v230 offset:35840
	ds_read_b128 v[198:201], v230 offset:36864
	ds_read_b128 v[202:205], v230 offset:37888
	ds_read_b128 v[206:209], v230 offset:38912
	ds_read_b128 v[232:235], v230 offset:39936
	global_load_lds_dwordx4 v158, s[46:47]
	s_mov_b32 m0, s9
	s_nop 0
	global_load_lds_dwordx4 v162, s[46:47]
	s_waitcnt vmcnt(8)
	s_waitcnt lgkmcnt(0)
	s_barrier
	s_setprio 1
	s_waitcnt lgkmcnt(0)
	v_mfma_f32_16x16x32_bf16 v[16:19], v[128:131], v[182:185], v[16:19]
	v_mfma_f32_16x16x32_bf16 v[28:31], v[136:139], v[182:185], v[28:31]
	v_mfma_f32_16x16x32_bf16 v[12:15], v[128:131], v[190:193], v[12:15]
	v_mfma_f32_16x16x32_bf16 v[8:11], v[136:139], v[190:193], v[8:11]
	v_mfma_f32_16x16x32_bf16 v[124:127], v[128:131], v[198:201], v[124:127]
	v_mfma_f32_16x16x32_bf16 v[120:123], v[136:139], v[198:201], v[120:123]
	v_mfma_f32_16x16x32_bf16 v[108:111], v[128:131], v[206:209], v[108:111]
	v_mfma_f32_16x16x32_bf16 v[104:107], v[136:139], v[206:209], v[104:107]
	v_mfma_f32_16x16x32_bf16 v[16:19], v[132:135], v[186:189], v[16:19]
	v_mfma_f32_16x16x32_bf16 v[28:31], v[140:143], v[186:189], v[28:31]
	v_mfma_f32_16x16x32_bf16 v[12:15], v[132:135], v[194:197], v[12:15]
	v_mfma_f32_16x16x32_bf16 v[8:11], v[140:143], v[194:197], v[8:11]
	v_mfma_f32_16x16x32_bf16 v[124:127], v[132:135], v[202:205], v[124:127]
	v_mfma_f32_16x16x32_bf16 v[120:123], v[140:143], v[202:205], v[120:123]
	v_mfma_f32_16x16x32_bf16 v[108:111], v[132:135], v[232:235], v[108:111]
	v_mfma_f32_16x16x32_bf16 v[104:107], v[140:143], v[232:235], v[104:107]
	s_setprio 0
	s_setprio 1
	v_mfma_f32_16x16x32_bf16 v[24:27], v[144:147], v[182:185], v[24:27]
	v_mfma_f32_16x16x32_bf16 v[20:23], v[174:177], v[182:185], v[20:23]
	v_mfma_f32_16x16x32_bf16 v[4:7], v[144:147], v[190:193], v[4:7]
	v_mfma_f32_16x16x32_bf16 v[0:3], v[174:177], v[190:193], v[0:3]
	v_mfma_f32_16x16x32_bf16 v[116:119], v[144:147], v[198:201], v[116:119]
	v_mfma_f32_16x16x32_bf16 v[112:115], v[174:177], v[198:201], v[112:115]
	v_mfma_f32_16x16x32_bf16 v[100:103], v[144:147], v[206:209], v[100:103]
	v_mfma_f32_16x16x32_bf16 v[96:99], v[174:177], v[206:209], v[96:99]
	v_mfma_f32_16x16x32_bf16 v[24:27], v[148:151], v[186:189], v[24:27]
	v_mfma_f32_16x16x32_bf16 v[20:23], v[178:181], v[186:189], v[20:23]
	v_mfma_f32_16x16x32_bf16 v[4:7], v[148:151], v[194:197], v[4:7]
	v_mfma_f32_16x16x32_bf16 v[0:3], v[178:181], v[194:197], v[0:3]
	v_mfma_f32_16x16x32_bf16 v[116:119], v[148:151], v[202:205], v[116:119]
	v_mfma_f32_16x16x32_bf16 v[112:115], v[178:181], v[202:205], v[112:115]
	v_mfma_f32_16x16x32_bf16 v[100:103], v[148:151], v[232:235], v[100:103]
	v_mfma_f32_16x16x32_bf16 v[96:99], v[178:181], v[232:235], v[96:99]
	s_setprio 0
	s_barrier
	s_add_u32 vcc_lo, s70, s6
	s_addc_u32 vcc_hi, s71, s7
	s_sub_u32 vcc_lo, vcc_lo, s26
	s_subb_u32 vcc_hi, vcc_hi, 0
	s_add_i32 m0, s3, 0x18000
	ds_read_b128 v[182:185], v230 offset:49152
	ds_read_b128 v[186:189], v230 offset:50176
	ds_read_b128 v[190:193], v230 offset:51200
	ds_read_b128 v[194:197], v230 offset:52224
	ds_read_b128 v[198:201], v230 offset:53248
	ds_read_b128 v[202:205], v230 offset:54272
	ds_read_b128 v[206:209], v230 offset:55296
	ds_read_b128 v[232:235], v230 offset:56320
	global_load_lds_dwordx4 v160, vcc
	s_add_i32 m0, s3, 0x1a000
	s_nop 0
	global_load_lds_dwordx4 v164, vcc
	s_add_u32 vcc_lo, vcc_lo, s26
	s_addc_u32 vcc_hi, vcc_hi, 0
	s_add_i32 m0, s3, 0x1c000
	s_nop 0
	global_load_lds_dwordx4 v160, vcc
	s_add_i32 m0, s3, 0x1e000
	s_nop 0
	global_load_lds_dwordx4 v164, vcc
	s_add_u32 vcc_lo, s46, s6
	s_addc_u32 vcc_hi, s47, s7
	s_sub_u32 vcc_lo, vcc_lo, s26
	s_subb_u32 vcc_hi, vcc_hi, 0
	s_mov_b32 m0, s30
	s_nop 0
	global_load_lds_dwordx4 v158, vcc
	s_mov_b32 m0, s31
	s_nop 0
	global_load_lds_dwordx4 v162, vcc
	s_add_u32 s44, s44, 0x100
	s_addc_u32 s45, s45, 0
	s_add_u32 s23, s23, 0x100
	s_addc_u32 s48, s48, 0
	s_cmp_ge_u32 s49, s88
	s_mov_b32 s46, s49
	s_waitcnt vmcnt(8)
	s_waitcnt lgkmcnt(0)
	s_barrier
	s_setprio 1
	s_waitcnt lgkmcnt(0)
	v_mfma_f32_16x16x32_bf16 v[92:95], v[128:131], v[182:185], v[92:95]
	v_mfma_f32_16x16x32_bf16 v[88:91], v[136:139], v[182:185], v[88:91]
	v_mfma_f32_16x16x32_bf16 v[76:79], v[128:131], v[190:193], v[76:79]
	v_mfma_f32_16x16x32_bf16 v[72:75], v[136:139], v[190:193], v[72:75]
	v_mfma_f32_16x16x32_bf16 v[60:63], v[128:131], v[198:201], v[60:63]
	v_mfma_f32_16x16x32_bf16 v[56:59], v[136:139], v[198:201], v[56:59]
	v_mfma_f32_16x16x32_bf16 v[44:47], v[128:131], v[206:209], v[44:47]
	v_mfma_f32_16x16x32_bf16 v[40:43], v[136:139], v[206:209], v[40:43]
	v_mfma_f32_16x16x32_bf16 v[92:95], v[132:135], v[186:189], v[92:95]
	v_mfma_f32_16x16x32_bf16 v[88:91], v[140:143], v[186:189], v[88:91]
	v_mfma_f32_16x16x32_bf16 v[76:79], v[132:135], v[194:197], v[76:79]
	v_mfma_f32_16x16x32_bf16 v[72:75], v[140:143], v[194:197], v[72:75]
	v_mfma_f32_16x16x32_bf16 v[60:63], v[132:135], v[202:205], v[60:63]
	v_mfma_f32_16x16x32_bf16 v[56:59], v[140:143], v[202:205], v[56:59]
	v_mfma_f32_16x16x32_bf16 v[44:47], v[132:135], v[232:235], v[44:47]
	v_mfma_f32_16x16x32_bf16 v[40:43], v[140:143], v[232:235], v[40:43]
	s_setprio 0
	s_setprio 1
	v_mfma_f32_16x16x32_bf16 v[84:87], v[144:147], v[182:185], v[84:87]
	v_mfma_f32_16x16x32_bf16 v[80:83], v[174:177], v[182:185], v[80:83]
	v_mfma_f32_16x16x32_bf16 v[68:71], v[144:147], v[190:193], v[68:71]
	v_mfma_f32_16x16x32_bf16 v[64:67], v[174:177], v[190:193], v[64:67]
	v_mfma_f32_16x16x32_bf16 v[52:55], v[144:147], v[198:201], v[52:55]
	v_mfma_f32_16x16x32_bf16 v[48:51], v[174:177], v[198:201], v[48:51]
	v_mfma_f32_16x16x32_bf16 v[36:39], v[144:147], v[206:209], v[36:39]
	v_mfma_f32_16x16x32_bf16 v[32:35], v[174:177], v[206:209], v[32:35]
	v_mfma_f32_16x16x32_bf16 v[84:87], v[148:151], v[186:189], v[84:87]
	v_mfma_f32_16x16x32_bf16 v[80:83], v[178:181], v[186:189], v[80:83]
	v_mfma_f32_16x16x32_bf16 v[68:71], v[148:151], v[194:197], v[68:71]
	v_mfma_f32_16x16x32_bf16 v[64:67], v[178:181], v[194:197], v[64:67]
	v_mfma_f32_16x16x32_bf16 v[52:55], v[148:151], v[202:205], v[52:55]
	v_mfma_f32_16x16x32_bf16 v[48:51], v[178:181], v[202:205], v[48:51]
	v_mfma_f32_16x16x32_bf16 v[36:39], v[148:151], v[232:235], v[36:39]
	v_mfma_f32_16x16x32_bf16 v[32:35], v[178:181], v[232:235], v[32:35]
	s_setprio 0
	s_barrier
	s_cbranch_scc1 .LBB0_249
.LBB0_248:
	ds_read_b128 v[128:131], v236
	ds_read_b128 v[132:135], v236 offset:1024
	ds_read_b128 v[136:139], v236 offset:2048
	ds_read_b128 v[140:143], v236 offset:3072
	ds_read_b128 v[144:147], v237
	ds_read_b128 v[148:151], v237 offset:1024
	ds_read_b128 v[174:177], v237 offset:2048
	ds_read_b128 v[178:181], v237 offset:3072
	s_add_i32 m0, s50, 0xc000
	ds_read_b128 v[182:185], v230
	ds_read_b128 v[186:189], v230 offset:1024
	ds_read_b128 v[190:193], v230 offset:2048
	ds_read_b128 v[194:197], v230 offset:3072
	ds_read_b128 v[198:201], v230 offset:4096
	ds_read_b128 v[202:205], v230 offset:5120
	ds_read_b128 v[206:209], v230 offset:6144
	ds_read_b128 v[232:235], v230 offset:7168
	global_load_lds_dwordx4 v170, s[44:45]
	s_add_i32 m0, s50, 0xe000
	s_nop 0
	global_load_lds_dwordx4 v172, s[44:45]
	s_add_i32 s49, s46, 2
	s_add_u32 s69, s44, 0x80
	s_addc_u32 s47, s45, 0
	s_add_i32 s80, 0, 0x10000
	s_cmp_eq_u32 s90, s46
	s_cselect_b32 s47, s65, s47
	s_cselect_b32 s46, s64, s69
	s_cselect_b32 s71, s67, s48
	s_cselect_b32 s70, s66, s23
	s_add_i32 s69, 0, 0x14000
	s_waitcnt vmcnt(8)
	s_waitcnt lgkmcnt(0)
	s_barrier
	s_setprio 1
	s_waitcnt lgkmcnt(0)
	v_mfma_f32_16x16x32_bf16 v[16:19], v[128:131], v[182:185], v[16:19]
	v_mfma_f32_16x16x32_bf16 v[28:31], v[136:139], v[182:185], v[28:31]
	v_mfma_f32_16x16x32_bf16 v[12:15], v[128:131], v[190:193], v[12:15]
	v_mfma_f32_16x16x32_bf16 v[8:11], v[136:139], v[190:193], v[8:11]
	v_mfma_f32_16x16x32_bf16 v[124:127], v[128:131], v[198:201], v[124:127]
	v_mfma_f32_16x16x32_bf16 v[120:123], v[136:139], v[198:201], v[120:123]
	v_mfma_f32_16x16x32_bf16 v[108:111], v[128:131], v[206:209], v[108:111]
	v_mfma_f32_16x16x32_bf16 v[104:107], v[136:139], v[206:209], v[104:107]
	v_mfma_f32_16x16x32_bf16 v[16:19], v[132:135], v[186:189], v[16:19]
	v_mfma_f32_16x16x32_bf16 v[28:31], v[140:143], v[186:189], v[28:31]
	v_mfma_f32_16x16x32_bf16 v[12:15], v[132:135], v[194:197], v[12:15]
	v_mfma_f32_16x16x32_bf16 v[8:11], v[140:143], v[194:197], v[8:11]
	v_mfma_f32_16x16x32_bf16 v[124:127], v[132:135], v[202:205], v[124:127]
	v_mfma_f32_16x16x32_bf16 v[120:123], v[140:143], v[202:205], v[120:123]
	v_mfma_f32_16x16x32_bf16 v[108:111], v[132:135], v[232:235], v[108:111]
	v_mfma_f32_16x16x32_bf16 v[104:107], v[140:143], v[232:235], v[104:107]
	s_setprio 0
	s_setprio 1
	v_mfma_f32_16x16x32_bf16 v[24:27], v[144:147], v[182:185], v[24:27]
	v_mfma_f32_16x16x32_bf16 v[20:23], v[174:177], v[182:185], v[20:23]
	v_mfma_f32_16x16x32_bf16 v[4:7], v[144:147], v[190:193], v[4:7]
	v_mfma_f32_16x16x32_bf16 v[0:3], v[174:177], v[190:193], v[0:3]
	v_mfma_f32_16x16x32_bf16 v[116:119], v[144:147], v[198:201], v[116:119]
	v_mfma_f32_16x16x32_bf16 v[112:115], v[174:177], v[198:201], v[112:115]
	v_mfma_f32_16x16x32_bf16 v[100:103], v[144:147], v[206:209], v[100:103]
	v_mfma_f32_16x16x32_bf16 v[96:99], v[174:177], v[206:209], v[96:99]
	v_mfma_f32_16x16x32_bf16 v[24:27], v[148:151], v[186:189], v[24:27]
	v_mfma_f32_16x16x32_bf16 v[20:23], v[178:181], v[186:189], v[20:23]
	v_mfma_f32_16x16x32_bf16 v[4:7], v[148:151], v[194:197], v[4:7]
	v_mfma_f32_16x16x32_bf16 v[0:3], v[178:181], v[194:197], v[0:3]
	v_mfma_f32_16x16x32_bf16 v[116:119], v[148:151], v[202:205], v[116:119]
	v_mfma_f32_16x16x32_bf16 v[112:115], v[178:181], v[202:205], v[112:115]
	v_mfma_f32_16x16x32_bf16 v[100:103], v[148:151], v[232:235], v[100:103]
	v_mfma_f32_16x16x32_bf16 v[96:99], v[178:181], v[232:235], v[96:99]
	s_setprio 0
	s_barrier
	s_add_i32 s80, s80, s3
	s_mov_b32 m0, s80
	ds_read_b128 v[182:185], v230 offset:16384
	ds_read_b128 v[186:189], v230 offset:17408
	ds_read_b128 v[190:193], v230 offset:18432
	ds_read_b128 v[194:197], v230 offset:19456
	ds_read_b128 v[198:201], v230 offset:20480
	ds_read_b128 v[202:205], v230 offset:21504
	ds_read_b128 v[206:209], v230 offset:22528
	ds_read_b128 v[232:235], v230 offset:23552
	global_load_lds_dwordx4 v160, s[70:71]
	s_add_i32 m0, s80, 0x2000
	s_add_i32 s69, s69, s3
	global_load_lds_dwordx4 v164, s[70:71]
	s_add_u32 s70, s70, s26
	s_addc_u32 s71, s71, 0
	s_mov_b32 m0, s69
	s_nop 0
	global_load_lds_dwordx4 v160, s[70:71]
	s_add_i32 m0, s69, 0x2000
	s_nop 0
	global_load_lds_dwordx4 v164, s[70:71]
	s_mov_b32 m0, s50
	s_nop 0
	global_load_lds_dwordx4 v158, s[46:47]
	s_mov_b32 m0, s51
	s_nop 0
	global_load_lds_dwordx4 v162, s[46:47]
	s_waitcnt vmcnt(8)
	s_waitcnt lgkmcnt(0)
	s_barrier
	s_setprio 1
	s_waitcnt lgkmcnt(0)
	v_mfma_f32_16x16x32_bf16 v[92:95], v[128:131], v[182:185], v[92:95]
	v_mfma_f32_16x16x32_bf16 v[88:91], v[136:139], v[182:185], v[88:91]
	v_mfma_f32_16x16x32_bf16 v[76:79], v[128:131], v[190:193], v[76:79]
	v_mfma_f32_16x16x32_bf16 v[72:75], v[136:139], v[190:193], v[72:75]
	v_mfma_f32_16x16x32_bf16 v[60:63], v[128:131], v[198:201], v[60:63]
	v_mfma_f32_16x16x32_bf16 v[56:59], v[136:139], v[198:201], v[56:59]
	v_mfma_f32_16x16x32_bf16 v[44:47], v[128:131], v[206:209], v[44:47]
	v_mfma_f32_16x16x32_bf16 v[40:43], v[136:139], v[206:209], v[40:43]
	v_mfma_f32_16x16x32_bf16 v[92:95], v[132:135], v[186:189], v[92:95]
	v_mfma_f32_16x16x32_bf16 v[88:91], v[140:143], v[186:189], v[88:91]
	v_mfma_f32_16x16x32_bf16 v[76:79], v[132:135], v[194:197], v[76:79]
	v_mfma_f32_16x16x32_bf16 v[72:75], v[140:143], v[194:197], v[72:75]
	v_mfma_f32_16x16x32_bf16 v[60:63], v[132:135], v[202:205], v[60:63]
	v_mfma_f32_16x16x32_bf16 v[56:59], v[140:143], v[202:205], v[56:59]
	v_mfma_f32_16x16x32_bf16 v[44:47], v[132:135], v[232:235], v[44:47]
	v_mfma_f32_16x16x32_bf16 v[40:43], v[140:143], v[232:235], v[40:43]
	s_setprio 0
	s_setprio 1
	v_mfma_f32_16x16x32_bf16 v[84:87], v[144:147], v[182:185], v[84:87]
	v_mfma_f32_16x16x32_bf16 v[80:83], v[174:177], v[182:185], v[80:83]
	v_mfma_f32_16x16x32_bf16 v[68:71], v[144:147], v[190:193], v[68:71]
	v_mfma_f32_16x16x32_bf16 v[64:67], v[174:177], v[190:193], v[64:67]
	v_mfma_f32_16x16x32_bf16 v[52:55], v[144:147], v[198:201], v[52:55]
	v_mfma_f32_16x16x32_bf16 v[48:51], v[174:177], v[198:201], v[48:51]
	v_mfma_f32_16x16x32_bf16 v[36:39], v[144:147], v[206:209], v[36:39]
	v_mfma_f32_16x16x32_bf16 v[32:35], v[174:177], v[206:209], v[32:35]
	v_mfma_f32_16x16x32_bf16 v[84:87], v[148:151], v[186:189], v[84:87]
	v_mfma_f32_16x16x32_bf16 v[80:83], v[178:181], v[186:189], v[80:83]
	v_mfma_f32_16x16x32_bf16 v[68:71], v[148:151], v[194:197], v[68:71]
	v_mfma_f32_16x16x32_bf16 v[64:67], v[178:181], v[194:197], v[64:67]
	v_mfma_f32_16x16x32_bf16 v[52:55], v[148:151], v[202:205], v[52:55]
	v_mfma_f32_16x16x32_bf16 v[48:51], v[178:181], v[202:205], v[48:51]
	v_mfma_f32_16x16x32_bf16 v[36:39], v[148:151], v[232:235], v[36:39]
	v_mfma_f32_16x16x32_bf16 v[32:35], v[178:181], v[232:235], v[32:35]
	s_setprio 0
	s_barrier
	ds_read_b128 v[128:131], v238
	ds_read_b128 v[132:135], v238 offset:1024
	ds_read_b128 v[136:139], v238 offset:2048
	ds_read_b128 v[140:143], v238 offset:3072
	ds_read_b128 v[144:147], v239
	ds_read_b128 v[148:151], v239 offset:1024
	ds_read_b128 v[174:177], v239 offset:2048
	ds_read_b128 v[178:181], v239 offset:3072
	s_add_u32 s46, s46, s26
	s_addc_u32 s47, s47, 0
	s_mov_b32 m0, s8
	ds_read_b128 v[182:185], v230 offset:32768
	ds_read_b128 v[186:189], v230 offset:33792
	ds_read_b128 v[190:193], v230 offset:34816
	ds_read_b128 v[194:197], v230 offset:35840
	ds_read_b128 v[198:201], v230 offset:36864
	ds_read_b128 v[202:205], v230 offset:37888
	ds_read_b128 v[206:209], v230 offset:38912
	ds_read_b128 v[232:235], v230 offset:39936
	global_load_lds_dwordx4 v158, s[46:47]
	s_mov_b32 m0, s9
	s_nop 0
	global_load_lds_dwordx4 v162, s[46:47]
	s_waitcnt vmcnt(8)
	s_waitcnt lgkmcnt(0)
	s_barrier
	s_setprio 1
	s_waitcnt lgkmcnt(0)
	v_mfma_f32_16x16x32_bf16 v[16:19], v[128:131], v[182:185], v[16:19]
	v_mfma_f32_16x16x32_bf16 v[28:31], v[136:139], v[182:185], v[28:31]
	v_mfma_f32_16x16x32_bf16 v[12:15], v[128:131], v[190:193], v[12:15]
	v_mfma_f32_16x16x32_bf16 v[8:11], v[136:139], v[190:193], v[8:11]
	v_mfma_f32_16x16x32_bf16 v[124:127], v[128:131], v[198:201], v[124:127]
	v_mfma_f32_16x16x32_bf16 v[120:123], v[136:139], v[198:201], v[120:123]
	v_mfma_f32_16x16x32_bf16 v[108:111], v[128:131], v[206:209], v[108:111]
	v_mfma_f32_16x16x32_bf16 v[104:107], v[136:139], v[206:209], v[104:107]
	v_mfma_f32_16x16x32_bf16 v[16:19], v[132:135], v[186:189], v[16:19]
	v_mfma_f32_16x16x32_bf16 v[28:31], v[140:143], v[186:189], v[28:31]
	v_mfma_f32_16x16x32_bf16 v[12:15], v[132:135], v[194:197], v[12:15]
	v_mfma_f32_16x16x32_bf16 v[8:11], v[140:143], v[194:197], v[8:11]
	v_mfma_f32_16x16x32_bf16 v[124:127], v[132:135], v[202:205], v[124:127]
	v_mfma_f32_16x16x32_bf16 v[120:123], v[140:143], v[202:205], v[120:123]
	v_mfma_f32_16x16x32_bf16 v[108:111], v[132:135], v[232:235], v[108:111]
	v_mfma_f32_16x16x32_bf16 v[104:107], v[140:143], v[232:235], v[104:107]
	s_setprio 0
	s_setprio 1
	v_mfma_f32_16x16x32_bf16 v[24:27], v[144:147], v[182:185], v[24:27]
	v_mfma_f32_16x16x32_bf16 v[20:23], v[174:177], v[182:185], v[20:23]
	v_mfma_f32_16x16x32_bf16 v[4:7], v[144:147], v[190:193], v[4:7]
	v_mfma_f32_16x16x32_bf16 v[0:3], v[174:177], v[190:193], v[0:3]
	v_mfma_f32_16x16x32_bf16 v[116:119], v[144:147], v[198:201], v[116:119]
	v_mfma_f32_16x16x32_bf16 v[112:115], v[174:177], v[198:201], v[112:115]
	v_mfma_f32_16x16x32_bf16 v[100:103], v[144:147], v[206:209], v[100:103]
	v_mfma_f32_16x16x32_bf16 v[96:99], v[174:177], v[206:209], v[96:99]
	v_mfma_f32_16x16x32_bf16 v[24:27], v[148:151], v[186:189], v[24:27]
	v_mfma_f32_16x16x32_bf16 v[20:23], v[178:181], v[186:189], v[20:23]
	v_mfma_f32_16x16x32_bf16 v[4:7], v[148:151], v[194:197], v[4:7]
	v_mfma_f32_16x16x32_bf16 v[0:3], v[178:181], v[194:197], v[0:3]
	v_mfma_f32_16x16x32_bf16 v[116:119], v[148:151], v[202:205], v[116:119]
	v_mfma_f32_16x16x32_bf16 v[112:115], v[178:181], v[202:205], v[112:115]
	v_mfma_f32_16x16x32_bf16 v[100:103], v[148:151], v[232:235], v[100:103]
	v_mfma_f32_16x16x32_bf16 v[96:99], v[178:181], v[232:235], v[96:99]
	s_setprio 0
	s_barrier
	s_add_u32 vcc_lo, s70, s6
	s_addc_u32 vcc_hi, s71, s7
	s_sub_u32 vcc_lo, vcc_lo, s26
	s_subb_u32 vcc_hi, vcc_hi, 0
	s_add_i32 m0, s3, 0x18000
	ds_read_b128 v[182:185], v230 offset:49152
	ds_read_b128 v[186:189], v230 offset:50176
	ds_read_b128 v[190:193], v230 offset:51200
	ds_read_b128 v[194:197], v230 offset:52224
	ds_read_b128 v[198:201], v230 offset:53248
	ds_read_b128 v[202:205], v230 offset:54272
	ds_read_b128 v[206:209], v230 offset:55296
	ds_read_b128 v[232:235], v230 offset:56320
	global_load_lds_dwordx4 v160, vcc
	s_add_i32 m0, s3, 0x1a000
	s_nop 0
	global_load_lds_dwordx4 v164, vcc
	s_add_u32 vcc_lo, vcc_lo, s26
	s_addc_u32 vcc_hi, vcc_hi, 0
	s_add_i32 m0, s3, 0x1c000
	s_nop 0
	global_load_lds_dwordx4 v160, vcc
	s_add_i32 m0, s3, 0x1e000
	s_nop 0
	global_load_lds_dwordx4 v164, vcc
	s_add_u32 vcc_lo, s46, s6
	s_addc_u32 vcc_hi, s47, s7
	s_sub_u32 vcc_lo, vcc_lo, s26
	s_subb_u32 vcc_hi, vcc_hi, 0
	s_mov_b32 m0, s30
	s_nop 0
	global_load_lds_dwordx4 v158, vcc
	s_mov_b32 m0, s31
	s_nop 0
	global_load_lds_dwordx4 v162, vcc
	s_add_u32 s44, s44, 0x100
	s_addc_u32 s45, s45, 0
	s_add_u32 s23, s23, 0x100
	s_addc_u32 s48, s48, 0
	s_cmp_ge_u32 s49, s88
	s_mov_b32 s46, s49
	s_waitcnt vmcnt(8)
	s_waitcnt lgkmcnt(0)
	s_barrier
	s_setprio 1
	s_waitcnt lgkmcnt(0)
	v_mfma_f32_16x16x32_bf16 v[92:95], v[128:131], v[182:185], v[92:95]
	v_mfma_f32_16x16x32_bf16 v[88:91], v[136:139], v[182:185], v[88:91]
	v_mfma_f32_16x16x32_bf16 v[76:79], v[128:131], v[190:193], v[76:79]
	v_mfma_f32_16x16x32_bf16 v[72:75], v[136:139], v[190:193], v[72:75]
	v_mfma_f32_16x16x32_bf16 v[60:63], v[128:131], v[198:201], v[60:63]
	v_mfma_f32_16x16x32_bf16 v[56:59], v[136:139], v[198:201], v[56:59]
	v_mfma_f32_16x16x32_bf16 v[44:47], v[128:131], v[206:209], v[44:47]
	v_mfma_f32_16x16x32_bf16 v[40:43], v[136:139], v[206:209], v[40:43]
	v_mfma_f32_16x16x32_bf16 v[92:95], v[132:135], v[186:189], v[92:95]
	v_mfma_f32_16x16x32_bf16 v[88:91], v[140:143], v[186:189], v[88:91]
	v_mfma_f32_16x16x32_bf16 v[76:79], v[132:135], v[194:197], v[76:79]
	v_mfma_f32_16x16x32_bf16 v[72:75], v[140:143], v[194:197], v[72:75]
	v_mfma_f32_16x16x32_bf16 v[60:63], v[132:135], v[202:205], v[60:63]
	v_mfma_f32_16x16x32_bf16 v[56:59], v[140:143], v[202:205], v[56:59]
	v_mfma_f32_16x16x32_bf16 v[44:47], v[132:135], v[232:235], v[44:47]
	v_mfma_f32_16x16x32_bf16 v[40:43], v[140:143], v[232:235], v[40:43]
	s_setprio 0
	s_setprio 1
	v_mfma_f32_16x16x32_bf16 v[84:87], v[144:147], v[182:185], v[84:87]
	v_mfma_f32_16x16x32_bf16 v[80:83], v[174:177], v[182:185], v[80:83]
	v_mfma_f32_16x16x32_bf16 v[68:71], v[144:147], v[190:193], v[68:71]
	v_mfma_f32_16x16x32_bf16 v[64:67], v[174:177], v[190:193], v[64:67]
	v_mfma_f32_16x16x32_bf16 v[52:55], v[144:147], v[198:201], v[52:55]
	v_mfma_f32_16x16x32_bf16 v[48:51], v[174:177], v[198:201], v[48:51]
	v_mfma_f32_16x16x32_bf16 v[36:39], v[144:147], v[206:209], v[36:39]
	v_mfma_f32_16x16x32_bf16 v[32:35], v[174:177], v[206:209], v[32:35]
	v_mfma_f32_16x16x32_bf16 v[84:87], v[148:151], v[186:189], v[84:87]
	v_mfma_f32_16x16x32_bf16 v[80:83], v[178:181], v[186:189], v[80:83]
	v_mfma_f32_16x16x32_bf16 v[68:71], v[148:151], v[194:197], v[68:71]
	v_mfma_f32_16x16x32_bf16 v[64:67], v[178:181], v[194:197], v[64:67]
	v_mfma_f32_16x16x32_bf16 v[52:55], v[148:151], v[202:205], v[52:55]
	v_mfma_f32_16x16x32_bf16 v[48:51], v[178:181], v[202:205], v[48:51]
	v_mfma_f32_16x16x32_bf16 v[36:39], v[148:151], v[232:235], v[36:39]
	v_mfma_f32_16x16x32_bf16 v[32:35], v[178:181], v[232:235], v[32:35]
	s_setprio 0
	s_barrier
	s_cbranch_scc0 .LBB0_248
